# v54 + the four K-loop heads aligned to 64 bytes
# speedup vs baseline: 1.0053x; 1.0053x over previous
.LBB0_113:
	s_add_u32 s20, s0, 0x100
	s_addc_u32 s21, s1, 0
	s_ashr_i32 s37, s36, 31
	s_lshl_b64 s[38:39], s[36:37], 20
	s_add_u32 s40, s16, s38
	s_addc_u32 s41, s17, s39
	s_and_b64 s[38:39], s[62:63], exec
	s_cselect_b32 s25, s41, s5
	s_cselect_b32 s37, s40, s4
	s_ashr_i32 s29, s28, 31
	s_lshl_b64 s[38:39], s[28:29], 20
	s_add_u32 s38, s3, s38
	s_addc_u32 s39, s22, s39
	s_and_b64 s[42:43], s[62:63], exec
	s_cselect_b32 s29, s39, s1
	s_cselect_b32 s64, s38, s0
	s_add_u32 s0, s4, 0x80080
	s_addc_u32 s1, s5, 0
	v_lshl_add_u64 v[138:139], s[0:1], 0, v[134:135]
	v_lshl_add_u64 v[140:141], s[0:1], 0, v[136:137]
	s_mov_b32 s65, -2
	s_mov_b64 s[0:1], 0
	s_add_u32 s42, s4, s0
	s_addc_u32 s43, s5, s1
	s_add_u32 s42, s42, 0x100
	s_addc_u32 s43, s43, 0
	s_add_u32 s66, s20, s0
	s_addc_u32 s67, s21, s1
	s_add_i32 s70, 0, 0x10000
	s_cmpk_eq_i32 s0, 0xf00
	s_cselect_b32 s45, s25, s43
	s_cselect_b32 s44, s37, s42
	v_add_u32_e32 v155, s70, v151
	s_cselect_b32 s43, s29, s67
	s_cselect_b32 s42, s64, s66
	s_add_i32 s71, 0, 0x14000
	ds_read_b128 v[142:145], v155
	ds_read_b128 v[146:149], v155 offset:1024
	ds_read_b128 v[156:159], v155 offset:2048
	ds_read_b128 v[160:163], v155 offset:3072
	v_add_u32_e32 v155, s71, v151
	ds_read_b128 v[164:167], v155
	ds_read_b128 v[168:171], v155 offset:1024
	ds_read_b128 v[172:175], v155 offset:2048
	ds_read_b128 v[176:179], v155 offset:3072
	v_lshl_add_u64 v[222:223], v[138:139], 0, s[0:1]
	s_add_i32 m0, s46, 0xc000
	ds_read_b128 v[180:183], v154
	ds_read_b128 v[184:187], v154 offset:1024
	ds_read_b128 v[188:191], v154 offset:2048
	ds_read_b128 v[192:195], v154 offset:3072
	ds_read_b128 v[196:199], v154 offset:4096
	ds_read_b128 v[210:213], v154 offset:5120
	ds_read_b128 v[214:217], v154 offset:6144
	ds_read_b128 v[218:221], v154 offset:7168
	global_load_lds_dwordx4 v[222:223], off
	v_lshl_add_u64 v[222:223], v[140:141], 0, s[0:1]
	s_add_i32 m0, s46, 0xe000
	s_nop 0
	global_load_lds_dwordx4 v[222:223], off
	s_waitcnt vmcnt(8)
	s_waitcnt lgkmcnt(0)
	s_barrier
	s_setprio 1
	v_mfma_f32_16x16x32_bf16 v[124:127], v[142:145], v[180:183], 0
	v_mfma_f32_16x16x32_bf16 v[120:123], v[156:159], v[180:183], 0
	v_mfma_f32_16x16x32_bf16 v[116:119], v[142:145], v[188:191], 0
	v_mfma_f32_16x16x32_bf16 v[112:115], v[156:159], v[188:191], 0
	v_mfma_f32_16x16x32_bf16 v[108:111], v[142:145], v[196:199], 0
	v_mfma_f32_16x16x32_bf16 v[104:107], v[156:159], v[196:199], 0
	v_mfma_f32_16x16x32_bf16 v[100:103], v[142:145], v[214:217], 0
	v_mfma_f32_16x16x32_bf16 v[96:99], v[156:159], v[214:217], 0
	v_mfma_f32_16x16x32_bf16 v[124:127], v[146:149], v[184:187], v[124:127]
	v_mfma_f32_16x16x32_bf16 v[120:123], v[160:163], v[184:187], v[120:123]
	v_mfma_f32_16x16x32_bf16 v[116:119], v[146:149], v[192:195], v[116:119]
	v_mfma_f32_16x16x32_bf16 v[112:115], v[160:163], v[192:195], v[112:115]
	v_mfma_f32_16x16x32_bf16 v[108:111], v[146:149], v[210:213], v[108:111]
	v_mfma_f32_16x16x32_bf16 v[104:107], v[160:163], v[210:213], v[104:107]
	v_mfma_f32_16x16x32_bf16 v[100:103], v[146:149], v[218:221], v[100:103]
	v_mfma_f32_16x16x32_bf16 v[96:99], v[160:163], v[218:221], v[96:99]
	v_mfma_f32_16x16x32_bf16 v[92:95], v[164:167], v[180:183], 0
	v_mfma_f32_16x16x32_bf16 v[88:91], v[172:175], v[180:183], 0
	v_mfma_f32_16x16x32_bf16 v[84:87], v[164:167], v[188:191], 0
	v_mfma_f32_16x16x32_bf16 v[80:83], v[172:175], v[188:191], 0
	v_mfma_f32_16x16x32_bf16 v[76:79], v[164:167], v[196:199], 0
	v_mfma_f32_16x16x32_bf16 v[72:75], v[172:175], v[196:199], 0
	v_mfma_f32_16x16x32_bf16 v[68:71], v[164:167], v[214:217], 0
	v_mfma_f32_16x16x32_bf16 v[64:67], v[172:175], v[214:217], 0
	v_mfma_f32_16x16x32_bf16 v[92:95], v[168:171], v[184:187], v[92:95]
	v_mfma_f32_16x16x32_bf16 v[88:91], v[176:179], v[184:187], v[88:91]
	v_mfma_f32_16x16x32_bf16 v[84:87], v[168:171], v[192:195], v[84:87]
	v_mfma_f32_16x16x32_bf16 v[80:83], v[176:179], v[192:195], v[80:83]
	v_mfma_f32_16x16x32_bf16 v[76:79], v[168:171], v[210:213], v[76:79]
	v_mfma_f32_16x16x32_bf16 v[72:75], v[176:179], v[210:213], v[72:75]
	v_mfma_f32_16x16x32_bf16 v[68:71], v[168:171], v[218:221], v[68:71]
	v_mfma_f32_16x16x32_bf16 v[64:67], v[176:179], v[218:221], v[64:67]
	s_setprio 0
	s_barrier
	s_add_i32 s66, s70, s2
	v_lshl_add_u64 v[222:223], s[42:43], 0, v[204:205]
	s_mov_b32 m0, s66
	ds_read_b128 v[180:183], v154 offset:16384
	ds_read_b128 v[184:187], v154 offset:17408
	ds_read_b128 v[188:191], v154 offset:18432
	ds_read_b128 v[192:195], v154 offset:19456
	ds_read_b128 v[196:199], v154 offset:20480
	ds_read_b128 v[210:213], v154 offset:21504
	ds_read_b128 v[214:217], v154 offset:22528
	ds_read_b128 v[218:221], v154 offset:23552
	global_load_lds_dwordx4 v[222:223], off
	s_add_i32 m0, s66, 0x2000
	s_add_u32 s66, s42, 0x80000
	v_lshl_add_u64 v[224:225], s[42:43], 0, v[128:129]
	s_addc_u32 s67, s43, 0
	s_add_i32 s70, s71, s2
	global_load_lds_dwordx4 v[224:225], off
	v_lshl_add_u64 v[226:227], s[66:67], 0, v[204:205]
	s_mov_b32 m0, s70
	v_lshl_add_u64 v[228:229], s[44:45], 0, v[130:131]
	global_load_lds_dwordx4 v[226:227], off
	v_lshl_add_u64 v[226:227], s[66:67], 0, v[128:129]
	s_add_i32 m0, s70, 0x2000
	s_nop 0
	global_load_lds_dwordx4 v[226:227], off
	v_lshl_add_u64 v[226:227], s[44:45], 0, v[132:133]
	s_mov_b32 m0, s46
	s_nop 0
	global_load_lds_dwordx4 v[226:227], off
	s_mov_b32 m0, s47
	s_nop 0
	global_load_lds_dwordx4 v[228:229], off
	s_waitcnt vmcnt(8)
	s_waitcnt lgkmcnt(0)
	s_barrier
	s_setprio 1
	v_mfma_f32_16x16x32_bf16 v[60:63], v[142:145], v[180:183], 0
	v_mfma_f32_16x16x32_bf16 v[56:59], v[156:159], v[180:183], 0
	v_mfma_f32_16x16x32_bf16 v[52:55], v[142:145], v[188:191], 0
	v_mfma_f32_16x16x32_bf16 v[48:51], v[156:159], v[188:191], 0
	v_mfma_f32_16x16x32_bf16 v[44:47], v[142:145], v[196:199], 0
	v_mfma_f32_16x16x32_bf16 v[40:43], v[156:159], v[196:199], 0
	v_mfma_f32_16x16x32_bf16 v[36:39], v[142:145], v[214:217], 0
	v_mfma_f32_16x16x32_bf16 v[32:35], v[156:159], v[214:217], 0
	v_mfma_f32_16x16x32_bf16 v[60:63], v[146:149], v[184:187], v[60:63]
	v_mfma_f32_16x16x32_bf16 v[56:59], v[160:163], v[184:187], v[56:59]
	v_mfma_f32_16x16x32_bf16 v[52:55], v[146:149], v[192:195], v[52:55]
	v_mfma_f32_16x16x32_bf16 v[48:51], v[160:163], v[192:195], v[48:51]
	v_mfma_f32_16x16x32_bf16 v[44:47], v[146:149], v[210:213], v[44:47]
	v_mfma_f32_16x16x32_bf16 v[40:43], v[160:163], v[210:213], v[40:43]
	v_mfma_f32_16x16x32_bf16 v[36:39], v[146:149], v[218:221], v[36:39]
	v_mfma_f32_16x16x32_bf16 v[32:35], v[160:163], v[218:221], v[32:35]
	v_mfma_f32_16x16x32_bf16 v[28:31], v[164:167], v[180:183], 0
	v_mfma_f32_16x16x32_bf16 v[24:27], v[172:175], v[180:183], 0
	v_mfma_f32_16x16x32_bf16 v[20:23], v[164:167], v[188:191], 0
	v_mfma_f32_16x16x32_bf16 v[16:19], v[172:175], v[188:191], 0
	v_mfma_f32_16x16x32_bf16 v[12:15], v[164:167], v[196:199], 0
	v_mfma_f32_16x16x32_bf16 v[8:11], v[172:175], v[196:199], 0
	v_mfma_f32_16x16x32_bf16 v[4:7], v[164:167], v[214:217], 0
	v_mfma_f32_16x16x32_bf16 v[0:3], v[172:175], v[214:217], 0
	v_mfma_f32_16x16x32_bf16 v[28:31], v[168:171], v[184:187], v[28:31]
	v_mfma_f32_16x16x32_bf16 v[24:27], v[176:179], v[184:187], v[24:27]
	v_mfma_f32_16x16x32_bf16 v[20:23], v[168:171], v[192:195], v[20:23]
	v_mfma_f32_16x16x32_bf16 v[16:19], v[176:179], v[192:195], v[16:19]
	v_mfma_f32_16x16x32_bf16 v[12:15], v[168:171], v[210:213], v[12:15]
	v_mfma_f32_16x16x32_bf16 v[8:11], v[176:179], v[210:213], v[8:11]
	v_mfma_f32_16x16x32_bf16 v[4:7], v[168:171], v[218:221], v[4:7]
	v_mfma_f32_16x16x32_bf16 v[0:3], v[176:179], v[218:221], v[0:3]
	s_setprio 0
	s_barrier
	s_add_i32 s66, 0, 0x18000
	v_add_u32_e32 v155, s66, v151
	s_add_i32 s67, 0, 0x1c000
	ds_read_b128 v[142:145], v155
	ds_read_b128 v[146:149], v155 offset:1024
	ds_read_b128 v[156:159], v155 offset:2048
	ds_read_b128 v[160:163], v155 offset:3072
	v_add_u32_e32 v155, s67, v151
	ds_read_b128 v[164:167], v155
	ds_read_b128 v[168:171], v155 offset:1024
	ds_read_b128 v[172:175], v155 offset:2048
	ds_read_b128 v[176:179], v155 offset:3072
	s_add_u32 s44, s44, 0x80000
	s_addc_u32 s45, s45, 0
	s_mov_b32 m0, s48
	v_lshl_add_u64 v[230:231], s[44:45], 0, v[132:133]
	ds_read_b128 v[180:183], v154 offset:32768
	ds_read_b128 v[184:187], v154 offset:33792
	ds_read_b128 v[188:191], v154 offset:34816
	ds_read_b128 v[192:195], v154 offset:35840
	ds_read_b128 v[196:199], v154 offset:36864
	ds_read_b128 v[210:213], v154 offset:37888
	ds_read_b128 v[214:217], v154 offset:38912
	ds_read_b128 v[218:221], v154 offset:39936
	global_load_lds_dwordx4 v[230:231], off
	v_lshl_add_u64 v[230:231], s[44:45], 0, v[130:131]
	s_mov_b32 m0, s49
	s_nop 0
	global_load_lds_dwordx4 v[230:231], off
	s_waitcnt vmcnt(8)
	s_waitcnt lgkmcnt(0)
	s_barrier
	s_setprio 1
	v_mfma_f32_16x16x32_bf16 v[124:127], v[142:145], v[180:183], v[124:127]
	v_mfma_f32_16x16x32_bf16 v[120:123], v[156:159], v[180:183], v[120:123]
	v_mfma_f32_16x16x32_bf16 v[116:119], v[142:145], v[188:191], v[116:119]
	v_mfma_f32_16x16x32_bf16 v[112:115], v[156:159], v[188:191], v[112:115]
	v_mfma_f32_16x16x32_bf16 v[108:111], v[142:145], v[196:199], v[108:111]
	v_mfma_f32_16x16x32_bf16 v[104:107], v[156:159], v[196:199], v[104:107]
	v_mfma_f32_16x16x32_bf16 v[100:103], v[142:145], v[214:217], v[100:103]
	v_mfma_f32_16x16x32_bf16 v[96:99], v[156:159], v[214:217], v[96:99]
	v_mfma_f32_16x16x32_bf16 v[124:127], v[146:149], v[184:187], v[124:127]
	v_mfma_f32_16x16x32_bf16 v[120:123], v[160:163], v[184:187], v[120:123]
	v_mfma_f32_16x16x32_bf16 v[116:119], v[146:149], v[192:195], v[116:119]
	v_mfma_f32_16x16x32_bf16 v[112:115], v[160:163], v[192:195], v[112:115]
	v_mfma_f32_16x16x32_bf16 v[108:111], v[146:149], v[210:213], v[108:111]
	v_mfma_f32_16x16x32_bf16 v[104:107], v[160:163], v[210:213], v[104:107]
	v_mfma_f32_16x16x32_bf16 v[100:103], v[146:149], v[218:221], v[100:103]
	v_mfma_f32_16x16x32_bf16 v[96:99], v[160:163], v[218:221], v[96:99]
	v_mfma_f32_16x16x32_bf16 v[92:95], v[164:167], v[180:183], v[92:95]
	v_mfma_f32_16x16x32_bf16 v[88:91], v[172:175], v[180:183], v[88:91]
	v_mfma_f32_16x16x32_bf16 v[84:87], v[164:167], v[188:191], v[84:87]
	v_mfma_f32_16x16x32_bf16 v[80:83], v[172:175], v[188:191], v[80:83]
	v_mfma_f32_16x16x32_bf16 v[76:79], v[164:167], v[196:199], v[76:79]
	v_mfma_f32_16x16x32_bf16 v[72:75], v[172:175], v[196:199], v[72:75]
	v_mfma_f32_16x16x32_bf16 v[68:71], v[164:167], v[214:217], v[68:71]
	v_mfma_f32_16x16x32_bf16 v[64:67], v[172:175], v[214:217], v[64:67]
	v_mfma_f32_16x16x32_bf16 v[92:95], v[168:171], v[184:187], v[92:95]
	v_mfma_f32_16x16x32_bf16 v[88:91], v[176:179], v[184:187], v[88:91]
	v_mfma_f32_16x16x32_bf16 v[84:87], v[168:171], v[192:195], v[84:87]
	v_mfma_f32_16x16x32_bf16 v[80:83], v[176:179], v[192:195], v[80:83]
	v_mfma_f32_16x16x32_bf16 v[76:79], v[168:171], v[210:213], v[76:79]
	v_mfma_f32_16x16x32_bf16 v[72:75], v[176:179], v[210:213], v[72:75]
	v_mfma_f32_16x16x32_bf16 v[68:71], v[168:171], v[218:221], v[68:71]
	v_mfma_f32_16x16x32_bf16 v[64:67], v[176:179], v[218:221], v[64:67]
	s_setprio 0
	s_barrier
	s_add_i32 s44, s66, s2
	v_lshl_add_u64 v[222:223], v[222:223], 0, s[12:13]
	s_mov_b32 m0, s44
	ds_read_b128 v[180:183], v154 offset:49152
	ds_read_b128 v[184:187], v154 offset:50176
	ds_read_b128 v[188:191], v154 offset:51200
	ds_read_b128 v[192:195], v154 offset:52224
	ds_read_b128 v[196:199], v154 offset:53248
	ds_read_b128 v[210:213], v154 offset:54272
	ds_read_b128 v[214:217], v154 offset:55296
	ds_read_b128 v[218:221], v154 offset:56320
	global_load_lds_dwordx4 v[222:223], off
	s_add_i32 m0, s44, 0x2000
	s_add_u32 s42, s42, 0x80080
	v_lshl_add_u64 v[222:223], v[224:225], 0, s[12:13]
	s_addc_u32 s43, s43, 0
	s_add_i32 s44, s67, s2
	global_load_lds_dwordx4 v[222:223], off
	v_lshl_add_u64 v[222:223], s[42:43], 0, v[204:205]
	s_mov_b32 m0, s44
	s_nop 0
	global_load_lds_dwordx4 v[222:223], off
	v_lshl_add_u64 v[222:223], s[42:43], 0, v[128:129]
	s_add_i32 m0, s44, 0x2000
	s_nop 0
	global_load_lds_dwordx4 v[222:223], off
	v_lshl_add_u64 v[222:223], v[226:227], 0, s[12:13]
	s_mov_b32 m0, s50
	s_nop 0
	global_load_lds_dwordx4 v[222:223], off
	v_lshl_add_u64 v[222:223], v[228:229], 0, s[12:13]
	s_mov_b32 m0, s51
	s_nop 0
	global_load_lds_dwordx4 v[222:223], off
	s_waitcnt vmcnt(8)
	s_waitcnt lgkmcnt(0)
	s_barrier
	s_setprio 1
	v_mfma_f32_16x16x32_bf16 v[60:63], v[142:145], v[180:183], v[60:63]
	v_mfma_f32_16x16x32_bf16 v[56:59], v[156:159], v[180:183], v[56:59]
	v_mfma_f32_16x16x32_bf16 v[52:55], v[142:145], v[188:191], v[52:55]
	v_mfma_f32_16x16x32_bf16 v[48:51], v[156:159], v[188:191], v[48:51]
	v_mfma_f32_16x16x32_bf16 v[44:47], v[142:145], v[196:199], v[44:47]
	v_mfma_f32_16x16x32_bf16 v[40:43], v[156:159], v[196:199], v[40:43]
	v_mfma_f32_16x16x32_bf16 v[36:39], v[142:145], v[214:217], v[36:39]
	v_mfma_f32_16x16x32_bf16 v[32:35], v[156:159], v[214:217], v[32:35]
	v_mfma_f32_16x16x32_bf16 v[60:63], v[146:149], v[184:187], v[60:63]
	v_mfma_f32_16x16x32_bf16 v[56:59], v[160:163], v[184:187], v[56:59]
	v_mfma_f32_16x16x32_bf16 v[52:55], v[146:149], v[192:195], v[52:55]
	v_mfma_f32_16x16x32_bf16 v[48:51], v[160:163], v[192:195], v[48:51]
	v_mfma_f32_16x16x32_bf16 v[44:47], v[146:149], v[210:213], v[44:47]
	v_mfma_f32_16x16x32_bf16 v[40:43], v[160:163], v[210:213], v[40:43]
	v_mfma_f32_16x16x32_bf16 v[36:39], v[146:149], v[218:221], v[36:39]
	v_mfma_f32_16x16x32_bf16 v[32:35], v[160:163], v[218:221], v[32:35]
	v_mfma_f32_16x16x32_bf16 v[28:31], v[164:167], v[180:183], v[28:31]
	v_mfma_f32_16x16x32_bf16 v[24:27], v[172:175], v[180:183], v[24:27]
	v_mfma_f32_16x16x32_bf16 v[20:23], v[164:167], v[188:191], v[20:23]
	v_mfma_f32_16x16x32_bf16 v[16:19], v[172:175], v[188:191], v[16:19]
	v_mfma_f32_16x16x32_bf16 v[12:15], v[164:167], v[196:199], v[12:15]
	v_mfma_f32_16x16x32_bf16 v[8:11], v[172:175], v[196:199], v[8:11]
	v_mfma_f32_16x16x32_bf16 v[4:7], v[164:167], v[214:217], v[4:7]
	v_mfma_f32_16x16x32_bf16 v[0:3], v[172:175], v[214:217], v[0:3]
	v_mfma_f32_16x16x32_bf16 v[28:31], v[168:171], v[184:187], v[28:31]
	v_mfma_f32_16x16x32_bf16 v[24:27], v[176:179], v[184:187], v[24:27]
	v_mfma_f32_16x16x32_bf16 v[20:23], v[168:171], v[192:195], v[20:23]
	v_mfma_f32_16x16x32_bf16 v[16:19], v[176:179], v[192:195], v[16:19]
	v_mfma_f32_16x16x32_bf16 v[12:15], v[168:171], v[210:213], v[12:15]
	v_mfma_f32_16x16x32_bf16 v[8:11], v[176:179], v[210:213], v[8:11]
	v_mfma_f32_16x16x32_bf16 v[4:7], v[168:171], v[218:221], v[4:7]
	v_mfma_f32_16x16x32_bf16 v[0:3], v[176:179], v[218:221], v[0:3]
	s_setprio 0
	s_barrier
	s_add_i32 s65, s65, 2
	s_add_u32 s0, s0, 0x100
	s_addc_u32 s1, s1, 0
	s_cmp_gt_u32 s65, 29
	s_cbranch_scc1 .Lpeel_exit_114
	.p2align 6

.LBB0_182:
	s_add_u32 s0, s0, 0x80
	s_addc_u32 s1, s1, 0
	s_add_u32 s21, s36, 0x100
	s_addc_u32 s22, s37, 0
	s_mov_b32 s4, 0
	s_add_i32 s25, s4, 2
	s_add_u32 s28, s0, 0x80
	s_addc_u32 s5, s1, 0
	s_add_i32 s36, 0, 0x10000
	s_cmp_eq_u32 s63, s4
	s_cselect_b32 s5, s49, s5
	s_cselect_b32 s4, s48, s28
	s_cselect_b32 s29, s51, s22
	s_cselect_b32 s28, s50, s21
	s_add_i32 s37, 0, 0x14000
	v_add_u32_e32 v100, s36, v249
	v_add_u32_e32 v156, s37, v249
	ds_read_b128 v[88:91], v100
	ds_read_b128 v[92:95], v100 offset:1024
	ds_read_b128 v[96:99], v100 offset:2048
	ds_read_b128 v[100:103], v100 offset:3072
	s_waitcnt lgkmcnt(0)
	ds_read_b128 v[144:147], v156
	ds_read_b128 v[148:151], v156 offset:1024
	ds_read_b128 v[152:155], v156 offset:2048
	ds_read_b128 v[156:159], v156 offset:3072
	v_lshl_add_u64 v[192:193], s[0:1], 0, v[216:217]
	s_add_i32 m0, s3, 0xc000
	ds_read_b128 v[160:163], v251
	ds_read_b128 v[164:167], v251 offset:1024
	ds_read_b128 v[168:171], v251 offset:2048
	ds_read_b128 v[172:175], v251 offset:3072
	ds_read_b128 v[176:179], v251 offset:4096
	ds_read_b128 v[180:183], v251 offset:5120
	ds_read_b128 v[184:187], v251 offset:6144
	ds_read_b128 v[188:191], v251 offset:7168
	global_load_lds_dwordx4 v[192:193], off
	v_lshl_add_u64 v[192:193], s[0:1], 0, v[218:219]
	s_add_i32 m0, s3, 0xe000
	s_nop 0
	global_load_lds_dwordx4 v[192:193], off
	s_waitcnt vmcnt(8)
	s_waitcnt lgkmcnt(0)
	s_barrier
	s_setprio 1
	v_mfma_f32_16x16x32_bf16 v[140:143], v[88:91], v[160:163], 0
	v_mfma_f32_16x16x32_bf16 v[136:139], v[96:99], v[160:163], 0
	v_mfma_f32_16x16x32_bf16 v[124:127], v[88:91], v[168:171], 0
	v_mfma_f32_16x16x32_bf16 v[120:123], v[96:99], v[168:171], 0
	v_mfma_f32_16x16x32_bf16 v[108:111], v[88:91], v[176:179], 0
	v_mfma_f32_16x16x32_bf16 v[104:107], v[96:99], v[176:179], 0
	v_mfma_f32_16x16x32_bf16 v[76:79], v[88:91], v[184:187], 0
	v_mfma_f32_16x16x32_bf16 v[72:75], v[96:99], v[184:187], 0
	v_mfma_f32_16x16x32_bf16 v[140:143], v[92:95], v[164:167], v[140:143]
	v_mfma_f32_16x16x32_bf16 v[136:139], v[100:103], v[164:167], v[136:139]
	v_mfma_f32_16x16x32_bf16 v[124:127], v[92:95], v[172:175], v[124:127]
	v_mfma_f32_16x16x32_bf16 v[120:123], v[100:103], v[172:175], v[120:123]
	v_mfma_f32_16x16x32_bf16 v[108:111], v[92:95], v[180:183], v[108:111]
	v_mfma_f32_16x16x32_bf16 v[104:107], v[100:103], v[180:183], v[104:107]
	v_mfma_f32_16x16x32_bf16 v[76:79], v[92:95], v[188:191], v[76:79]
	v_mfma_f32_16x16x32_bf16 v[72:75], v[100:103], v[188:191], v[72:75]
	v_mfma_f32_16x16x32_bf16 v[132:135], v[144:147], v[160:163], 0
	v_mfma_f32_16x16x32_bf16 v[128:131], v[152:155], v[160:163], 0
	v_mfma_f32_16x16x32_bf16 v[116:119], v[144:147], v[168:171], 0
	v_mfma_f32_16x16x32_bf16 v[112:115], v[152:155], v[168:171], 0
	v_mfma_f32_16x16x32_bf16 v[84:87], v[144:147], v[176:179], 0
	v_mfma_f32_16x16x32_bf16 v[80:83], v[152:155], v[176:179], 0
	v_mfma_f32_16x16x32_bf16 v[68:71], v[144:147], v[184:187], 0
	v_mfma_f32_16x16x32_bf16 v[64:67], v[152:155], v[184:187], 0
	v_mfma_f32_16x16x32_bf16 v[132:135], v[148:151], v[164:167], v[132:135]
	v_mfma_f32_16x16x32_bf16 v[128:131], v[156:159], v[164:167], v[128:131]
	v_mfma_f32_16x16x32_bf16 v[116:119], v[148:151], v[172:175], v[116:119]
	v_mfma_f32_16x16x32_bf16 v[112:115], v[156:159], v[172:175], v[112:115]
	v_mfma_f32_16x16x32_bf16 v[84:87], v[148:151], v[180:183], v[84:87]
	v_mfma_f32_16x16x32_bf16 v[80:83], v[156:159], v[180:183], v[80:83]
	v_mfma_f32_16x16x32_bf16 v[68:71], v[148:151], v[188:191], v[68:71]
	v_mfma_f32_16x16x32_bf16 v[64:67], v[156:159], v[188:191], v[64:67]
	s_setprio 0
	s_barrier
	s_add_i32 s36, s36, s2
	v_lshl_add_u64 v[192:193], s[28:29], 0, v[204:205]
	s_mov_b32 m0, s36
	ds_read_b128 v[160:163], v251 offset:16384
	ds_read_b128 v[164:167], v251 offset:17408
	ds_read_b128 v[168:171], v251 offset:18432
	ds_read_b128 v[172:175], v251 offset:19456
	ds_read_b128 v[176:179], v251 offset:20480
	ds_read_b128 v[180:183], v251 offset:21504
	ds_read_b128 v[184:187], v251 offset:22528
	ds_read_b128 v[188:191], v251 offset:23552
	global_load_lds_dwordx4 v[192:193], off
	s_add_i32 m0, s36, 0x2000
	v_lshl_add_u64 v[194:195], s[28:29], 0, v[210:211]
	s_add_u32 s28, s28, s10
	s_addc_u32 s29, s29, 0
	s_add_i32 s36, s37, s2
	global_load_lds_dwordx4 v[194:195], off
	v_lshl_add_u64 v[196:197], s[28:29], 0, v[204:205]
	s_mov_b32 m0, s36
	v_lshl_add_u64 v[198:199], s[28:29], 0, v[210:211]
	global_load_lds_dwordx4 v[196:197], off
	s_add_i32 m0, s36, 0x2000
	v_lshl_add_u64 v[220:221], s[4:5], 0, v[214:215]
	global_load_lds_dwordx4 v[198:199], off
	s_mov_b32 m0, s3
	v_lshl_add_u64 v[222:223], s[4:5], 0, v[212:213]
	global_load_lds_dwordx4 v[220:221], off
	s_mov_b32 m0, s52
	s_nop 0
	global_load_lds_dwordx4 v[222:223], off
	s_waitcnt vmcnt(8)
	s_waitcnt lgkmcnt(0)
	s_barrier
	s_setprio 1
	v_mfma_f32_16x16x32_bf16 v[60:63], v[88:91], v[160:163], 0
	v_mfma_f32_16x16x32_bf16 v[56:59], v[96:99], v[160:163], 0
	v_mfma_f32_16x16x32_bf16 v[44:47], v[88:91], v[168:171], 0
	v_mfma_f32_16x16x32_bf16 v[40:43], v[96:99], v[168:171], 0
	v_mfma_f32_16x16x32_bf16 v[28:31], v[88:91], v[176:179], 0
	v_mfma_f32_16x16x32_bf16 v[24:27], v[96:99], v[176:179], 0
	v_mfma_f32_16x16x32_bf16 v[12:15], v[88:91], v[184:187], 0
	v_mfma_f32_16x16x32_bf16 v[8:11], v[96:99], v[184:187], 0
	v_mfma_f32_16x16x32_bf16 v[60:63], v[92:95], v[164:167], v[60:63]
	v_mfma_f32_16x16x32_bf16 v[56:59], v[100:103], v[164:167], v[56:59]
	v_mfma_f32_16x16x32_bf16 v[44:47], v[92:95], v[172:175], v[44:47]
	v_mfma_f32_16x16x32_bf16 v[40:43], v[100:103], v[172:175], v[40:43]
	v_mfma_f32_16x16x32_bf16 v[28:31], v[92:95], v[180:183], v[28:31]
	v_mfma_f32_16x16x32_bf16 v[24:27], v[100:103], v[180:183], v[24:27]
	v_mfma_f32_16x16x32_bf16 v[12:15], v[92:95], v[188:191], v[12:15]
	v_mfma_f32_16x16x32_bf16 v[8:11], v[100:103], v[188:191], v[8:11]
	v_mfma_f32_16x16x32_bf16 v[52:55], v[144:147], v[160:163], 0
	v_mfma_f32_16x16x32_bf16 v[48:51], v[152:155], v[160:163], 0
	v_mfma_f32_16x16x32_bf16 v[36:39], v[144:147], v[168:171], 0
	v_mfma_f32_16x16x32_bf16 v[32:35], v[152:155], v[168:171], 0
	v_mfma_f32_16x16x32_bf16 v[20:23], v[144:147], v[176:179], 0
	v_mfma_f32_16x16x32_bf16 v[16:19], v[152:155], v[176:179], 0
	v_mfma_f32_16x16x32_bf16 v[4:7], v[144:147], v[184:187], 0
	v_mfma_f32_16x16x32_bf16 v[0:3], v[152:155], v[184:187], 0
	v_mfma_f32_16x16x32_bf16 v[52:55], v[148:151], v[164:167], v[52:55]
	v_mfma_f32_16x16x32_bf16 v[48:51], v[156:159], v[164:167], v[48:51]
	v_mfma_f32_16x16x32_bf16 v[36:39], v[148:151], v[172:175], v[36:39]
	v_mfma_f32_16x16x32_bf16 v[32:35], v[156:159], v[172:175], v[32:35]
	v_mfma_f32_16x16x32_bf16 v[20:23], v[148:151], v[180:183], v[20:23]
	v_mfma_f32_16x16x32_bf16 v[16:19], v[156:159], v[180:183], v[16:19]
	v_mfma_f32_16x16x32_bf16 v[4:7], v[148:151], v[188:191], v[4:7]
	v_mfma_f32_16x16x32_bf16 v[0:3], v[156:159], v[188:191], v[0:3]
	s_setprio 0
	s_barrier
	s_add_i32 s28, 0, 0x18000
	s_add_i32 s29, 0, 0x1c000
	v_add_u32_e32 v100, s28, v249
	v_add_u32_e32 v156, s29, v249
	ds_read_b128 v[88:91], v100
	ds_read_b128 v[92:95], v100 offset:1024
	ds_read_b128 v[96:99], v100 offset:2048
	ds_read_b128 v[100:103], v100 offset:3072
	ds_read_b128 v[144:147], v156
	ds_read_b128 v[148:151], v156 offset:1024
	ds_read_b128 v[152:155], v156 offset:2048
	ds_read_b128 v[156:159], v156 offset:3072
	s_add_u32 s4, s4, s10
	s_addc_u32 s5, s5, 0
	s_mov_b32 m0, s53
	v_lshl_add_u64 v[224:225], s[4:5], 0, v[214:215]
	ds_read_b128 v[160:163], v251 offset:32768
	ds_read_b128 v[164:167], v251 offset:33792
	ds_read_b128 v[168:171], v251 offset:34816
	ds_read_b128 v[172:175], v251 offset:35840
	ds_read_b128 v[176:179], v251 offset:36864
	ds_read_b128 v[180:183], v251 offset:37888
	ds_read_b128 v[184:187], v251 offset:38912
	ds_read_b128 v[188:191], v251 offset:39936
	global_load_lds_dwordx4 v[224:225], off
	v_lshl_add_u64 v[224:225], s[4:5], 0, v[212:213]
	s_mov_b32 m0, s54
	s_nop 0
	global_load_lds_dwordx4 v[224:225], off
	s_waitcnt vmcnt(8)
	s_waitcnt lgkmcnt(0)
	s_barrier
	s_setprio 1
	v_mfma_f32_16x16x32_bf16 v[140:143], v[88:91], v[160:163], v[140:143]
	v_mfma_f32_16x16x32_bf16 v[136:139], v[96:99], v[160:163], v[136:139]
	v_mfma_f32_16x16x32_bf16 v[124:127], v[88:91], v[168:171], v[124:127]
	v_mfma_f32_16x16x32_bf16 v[120:123], v[96:99], v[168:171], v[120:123]
	v_mfma_f32_16x16x32_bf16 v[108:111], v[88:91], v[176:179], v[108:111]
	v_mfma_f32_16x16x32_bf16 v[104:107], v[96:99], v[176:179], v[104:107]
	v_mfma_f32_16x16x32_bf16 v[76:79], v[88:91], v[184:187], v[76:79]
	v_mfma_f32_16x16x32_bf16 v[72:75], v[96:99], v[184:187], v[72:75]
	v_mfma_f32_16x16x32_bf16 v[140:143], v[92:95], v[164:167], v[140:143]
	v_mfma_f32_16x16x32_bf16 v[136:139], v[100:103], v[164:167], v[136:139]
	v_mfma_f32_16x16x32_bf16 v[124:127], v[92:95], v[172:175], v[124:127]
	v_mfma_f32_16x16x32_bf16 v[120:123], v[100:103], v[172:175], v[120:123]
	v_mfma_f32_16x16x32_bf16 v[108:111], v[92:95], v[180:183], v[108:111]
	v_mfma_f32_16x16x32_bf16 v[104:107], v[100:103], v[180:183], v[104:107]
	v_mfma_f32_16x16x32_bf16 v[76:79], v[92:95], v[188:191], v[76:79]
	v_mfma_f32_16x16x32_bf16 v[72:75], v[100:103], v[188:191], v[72:75]
	v_mfma_f32_16x16x32_bf16 v[132:135], v[144:147], v[160:163], v[132:135]
	v_mfma_f32_16x16x32_bf16 v[128:131], v[152:155], v[160:163], v[128:131]
	v_mfma_f32_16x16x32_bf16 v[116:119], v[144:147], v[168:171], v[116:119]
	v_mfma_f32_16x16x32_bf16 v[112:115], v[152:155], v[168:171], v[112:115]
	v_mfma_f32_16x16x32_bf16 v[84:87], v[144:147], v[176:179], v[84:87]
	v_mfma_f32_16x16x32_bf16 v[80:83], v[152:155], v[176:179], v[80:83]
	v_mfma_f32_16x16x32_bf16 v[68:71], v[144:147], v[184:187], v[68:71]
	v_mfma_f32_16x16x32_bf16 v[64:67], v[152:155], v[184:187], v[64:67]
	v_mfma_f32_16x16x32_bf16 v[132:135], v[148:151], v[164:167], v[132:135]
	v_mfma_f32_16x16x32_bf16 v[128:131], v[156:159], v[164:167], v[128:131]
	v_mfma_f32_16x16x32_bf16 v[116:119], v[148:151], v[172:175], v[116:119]
	v_mfma_f32_16x16x32_bf16 v[112:115], v[156:159], v[172:175], v[112:115]
	v_mfma_f32_16x16x32_bf16 v[84:87], v[148:151], v[180:183], v[84:87]
	v_mfma_f32_16x16x32_bf16 v[80:83], v[156:159], v[180:183], v[80:83]
	v_mfma_f32_16x16x32_bf16 v[68:71], v[148:151], v[188:191], v[68:71]
	v_mfma_f32_16x16x32_bf16 v[64:67], v[156:159], v[188:191], v[64:67]
	s_setprio 0
	s_barrier
	s_add_i32 s4, s28, s2
	v_lshl_add_u64 v[192:193], v[192:193], 0, s[12:13]
	s_mov_b32 m0, s4
	ds_read_b128 v[160:163], v251 offset:49152
	ds_read_b128 v[164:167], v251 offset:50176
	ds_read_b128 v[168:171], v251 offset:51200
	ds_read_b128 v[172:175], v251 offset:52224
	ds_read_b128 v[176:179], v251 offset:53248
	ds_read_b128 v[180:183], v251 offset:54272
	ds_read_b128 v[184:187], v251 offset:55296
	ds_read_b128 v[188:191], v251 offset:56320
	global_load_lds_dwordx4 v[192:193], off
	v_lshl_add_u64 v[192:193], v[194:195], 0, s[12:13]
	s_add_i32 m0, s4, 0x2000
	s_add_i32 s4, s29, s2
	global_load_lds_dwordx4 v[192:193], off
	v_lshl_add_u64 v[192:193], v[196:197], 0, s[12:13]
	s_mov_b32 m0, s4
	s_nop 0
	global_load_lds_dwordx4 v[192:193], off
	v_lshl_add_u64 v[192:193], v[198:199], 0, s[12:13]
	s_add_i32 m0, s4, 0x2000
	s_nop 0
	global_load_lds_dwordx4 v[192:193], off
	v_lshl_add_u64 v[192:193], v[220:221], 0, s[12:13]
	s_mov_b32 m0, s55
	s_nop 0
	global_load_lds_dwordx4 v[192:193], off
	v_lshl_add_u64 v[192:193], v[222:223], 0, s[12:13]
	s_mov_b32 m0, s56
	s_nop 0
	global_load_lds_dwordx4 v[192:193], off
	s_waitcnt vmcnt(8)
	s_waitcnt lgkmcnt(0)
	s_barrier
	s_setprio 1
	v_mfma_f32_16x16x32_bf16 v[60:63], v[88:91], v[160:163], v[60:63]
	v_mfma_f32_16x16x32_bf16 v[56:59], v[96:99], v[160:163], v[56:59]
	v_mfma_f32_16x16x32_bf16 v[44:47], v[88:91], v[168:171], v[44:47]
	v_mfma_f32_16x16x32_bf16 v[40:43], v[96:99], v[168:171], v[40:43]
	v_mfma_f32_16x16x32_bf16 v[28:31], v[88:91], v[176:179], v[28:31]
	v_mfma_f32_16x16x32_bf16 v[24:27], v[96:99], v[176:179], v[24:27]
	v_mfma_f32_16x16x32_bf16 v[12:15], v[88:91], v[184:187], v[12:15]
	v_mfma_f32_16x16x32_bf16 v[8:11], v[96:99], v[184:187], v[8:11]
	v_mfma_f32_16x16x32_bf16 v[60:63], v[92:95], v[164:167], v[60:63]
	v_mfma_f32_16x16x32_bf16 v[56:59], v[100:103], v[164:167], v[56:59]
	v_mfma_f32_16x16x32_bf16 v[44:47], v[92:95], v[172:175], v[44:47]
	v_mfma_f32_16x16x32_bf16 v[40:43], v[100:103], v[172:175], v[40:43]
	v_mfma_f32_16x16x32_bf16 v[28:31], v[92:95], v[180:183], v[28:31]
	v_mfma_f32_16x16x32_bf16 v[24:27], v[100:103], v[180:183], v[24:27]
	v_mfma_f32_16x16x32_bf16 v[12:15], v[92:95], v[188:191], v[12:15]
	v_mfma_f32_16x16x32_bf16 v[8:11], v[100:103], v[188:191], v[8:11]
	v_mfma_f32_16x16x32_bf16 v[52:55], v[144:147], v[160:163], v[52:55]
	v_mfma_f32_16x16x32_bf16 v[48:51], v[152:155], v[160:163], v[48:51]
	v_mfma_f32_16x16x32_bf16 v[36:39], v[144:147], v[168:171], v[36:39]
	v_mfma_f32_16x16x32_bf16 v[32:35], v[152:155], v[168:171], v[32:35]
	v_mfma_f32_16x16x32_bf16 v[20:23], v[144:147], v[176:179], v[20:23]
	v_mfma_f32_16x16x32_bf16 v[16:19], v[152:155], v[176:179], v[16:19]
	v_mfma_f32_16x16x32_bf16 v[4:7], v[144:147], v[184:187], v[4:7]
	v_mfma_f32_16x16x32_bf16 v[0:3], v[152:155], v[184:187], v[0:3]
	v_mfma_f32_16x16x32_bf16 v[52:55], v[148:151], v[164:167], v[52:55]
	v_mfma_f32_16x16x32_bf16 v[48:51], v[156:159], v[164:167], v[48:51]
	v_mfma_f32_16x16x32_bf16 v[36:39], v[148:151], v[172:175], v[36:39]
	v_mfma_f32_16x16x32_bf16 v[32:35], v[156:159], v[172:175], v[32:35]
	v_mfma_f32_16x16x32_bf16 v[20:23], v[148:151], v[180:183], v[20:23]
	v_mfma_f32_16x16x32_bf16 v[16:19], v[156:159], v[180:183], v[16:19]
	v_mfma_f32_16x16x32_bf16 v[4:7], v[148:151], v[188:191], v[4:7]
	v_mfma_f32_16x16x32_bf16 v[0:3], v[156:159], v[188:191], v[0:3]
	s_setprio 0
	s_barrier
	s_add_u32 s0, s0, 0x100
	s_addc_u32 s1, s1, 0
	s_add_u32 s21, s21, 0x100
	s_addc_u32 s22, s22, 0
	s_cmp_ge_u32 s25, s62
	s_mov_b32 s4, s25
	s_cbranch_scc1 .Lpeel_exit_183
	.p2align 6

.LBB0_317:
	s_add_u32 s25, s0, 0x100
	s_addc_u32 s66, s1, 0
	s_ashr_i32 s39, s38, 31
	s_lshl_b64 s[36:37], s[38:39], 20
	s_add_u32 s42, s16, s36
	s_addc_u32 s43, s17, s37
	s_and_b64 s[36:37], s[62:63], exec
	s_cselect_b32 s39, s43, s3
	s_cselect_b32 s67, s42, s2
	s_ashr_i32 s35, s34, 31
	s_lshl_b64 s[36:37], s[34:35], 20
	s_add_u32 s40, s46, s36
	s_addc_u32 s41, s47, s37
	s_and_b64 s[36:37], s[62:63], exec
	s_cselect_b32 s35, s41, s1
	s_cselect_b32 s70, s40, s0
	s_add_u32 s0, s2, 0x80080
	s_addc_u32 s1, s3, 0
	v_lshl_add_u64 v[128:129], s[0:1], 0, v[150:151]
	v_lshl_add_u64 v[130:131], s[0:1], 0, v[152:153]
	s_mov_b32 s71, -2
	s_mov_b64 s[0:1], 0
	s_add_u32 s36, s2, s0
	s_addc_u32 s37, s3, s1
	s_add_u32 s36, s36, 0x100
	s_addc_u32 s37, s37, 0
	s_add_u32 s72, s25, s0
	s_addc_u32 s73, s66, s1
	s_add_i32 s74, 0, 0x10000
	s_cmpk_eq_i32 s0, 0xf00
	s_cselect_b32 s45, s39, s37
	s_cselect_b32 s44, s67, s36
	v_add_u32_e32 v154, s74, v159
	s_cselect_b32 s37, s35, s73
	s_cselect_b32 s36, s70, s72
	s_add_i32 s75, 0, 0x14000
	ds_read_b128 v[132:135], v154
	ds_read_b128 v[136:139], v154 offset:1024
	ds_read_b128 v[140:143], v154 offset:2048
	ds_read_b128 v[166:169], v154 offset:3072
	v_add_u32_e32 v154, s75, v159
	ds_read_b128 v[170:173], v154
	ds_read_b128 v[174:177], v154 offset:1024
	ds_read_b128 v[178:181], v154 offset:2048
	ds_read_b128 v[182:185], v154 offset:3072
	v_lshl_add_u64 v[154:155], v[128:129], 0, s[0:1]
	s_add_i32 m0, s7, 0xc000
	ds_read_b128 v[186:189], v165
	ds_read_b128 v[190:193], v165 offset:1024
	ds_read_b128 v[194:197], v165 offset:2048
	ds_read_b128 v[210:213], v165 offset:3072
	ds_read_b128 v[214:217], v165 offset:4096
	ds_read_b128 v[218:221], v165 offset:5120
	ds_read_b128 v[222:225], v165 offset:6144
	ds_read_b128 v[226:229], v165 offset:7168
	global_load_lds_dwordx4 v[154:155], off
	v_lshl_add_u64 v[154:155], v[130:131], 0, s[0:1]
	s_add_i32 m0, s7, 0xe000
	s_nop 0
	global_load_lds_dwordx4 v[154:155], off
	s_waitcnt vmcnt(8)
	s_waitcnt lgkmcnt(0)
	s_barrier
	s_setprio 1
	v_mfma_f32_16x16x32_bf16 v[124:127], v[132:135], v[186:189], 0
	v_mfma_f32_16x16x32_bf16 v[120:123], v[140:143], v[186:189], 0
	v_mfma_f32_16x16x32_bf16 v[116:119], v[132:135], v[194:197], 0
	v_mfma_f32_16x16x32_bf16 v[112:115], v[140:143], v[194:197], 0
	v_mfma_f32_16x16x32_bf16 v[108:111], v[132:135], v[214:217], 0
	v_mfma_f32_16x16x32_bf16 v[104:107], v[140:143], v[214:217], 0
	v_mfma_f32_16x16x32_bf16 v[100:103], v[132:135], v[222:225], 0
	v_mfma_f32_16x16x32_bf16 v[96:99], v[140:143], v[222:225], 0
	v_mfma_f32_16x16x32_bf16 v[124:127], v[136:139], v[190:193], v[124:127]
	v_mfma_f32_16x16x32_bf16 v[120:123], v[166:169], v[190:193], v[120:123]
	v_mfma_f32_16x16x32_bf16 v[116:119], v[136:139], v[210:213], v[116:119]
	v_mfma_f32_16x16x32_bf16 v[112:115], v[166:169], v[210:213], v[112:115]
	v_mfma_f32_16x16x32_bf16 v[108:111], v[136:139], v[218:221], v[108:111]
	v_mfma_f32_16x16x32_bf16 v[104:107], v[166:169], v[218:221], v[104:107]
	v_mfma_f32_16x16x32_bf16 v[100:103], v[136:139], v[226:229], v[100:103]
	v_mfma_f32_16x16x32_bf16 v[96:99], v[166:169], v[226:229], v[96:99]
	v_mfma_f32_16x16x32_bf16 v[92:95], v[170:173], v[186:189], 0
	v_mfma_f32_16x16x32_bf16 v[88:91], v[178:181], v[186:189], 0
	v_mfma_f32_16x16x32_bf16 v[84:87], v[170:173], v[194:197], 0
	v_mfma_f32_16x16x32_bf16 v[80:83], v[178:181], v[194:197], 0
	v_mfma_f32_16x16x32_bf16 v[76:79], v[170:173], v[214:217], 0
	v_mfma_f32_16x16x32_bf16 v[72:75], v[178:181], v[214:217], 0
	v_mfma_f32_16x16x32_bf16 v[68:71], v[170:173], v[222:225], 0
	v_mfma_f32_16x16x32_bf16 v[64:67], v[178:181], v[222:225], 0
	v_mfma_f32_16x16x32_bf16 v[92:95], v[174:177], v[190:193], v[92:95]
	v_mfma_f32_16x16x32_bf16 v[88:91], v[182:185], v[190:193], v[88:91]
	v_mfma_f32_16x16x32_bf16 v[84:87], v[174:177], v[210:213], v[84:87]
	v_mfma_f32_16x16x32_bf16 v[80:83], v[182:185], v[210:213], v[80:83]
	v_mfma_f32_16x16x32_bf16 v[76:79], v[174:177], v[218:221], v[76:79]
	v_mfma_f32_16x16x32_bf16 v[72:75], v[182:185], v[218:221], v[72:75]
	v_mfma_f32_16x16x32_bf16 v[68:71], v[174:177], v[226:229], v[68:71]
	v_mfma_f32_16x16x32_bf16 v[64:67], v[182:185], v[226:229], v[64:67]
	s_setprio 0
	s_barrier
	s_add_i32 s72, s74, s29
	v_lshl_add_u64 v[154:155], s[36:37], 0, v[204:205]
	s_mov_b32 m0, s72
	ds_read_b128 v[186:189], v165 offset:16384
	ds_read_b128 v[190:193], v165 offset:17408
	ds_read_b128 v[194:197], v165 offset:18432
	ds_read_b128 v[210:213], v165 offset:19456
	ds_read_b128 v[214:217], v165 offset:20480
	ds_read_b128 v[218:221], v165 offset:21504
	ds_read_b128 v[222:225], v165 offset:22528
	ds_read_b128 v[226:229], v165 offset:23552
	global_load_lds_dwordx4 v[154:155], off
	s_add_i32 m0, s72, 0x2000
	s_add_u32 s72, s36, 0x80000
	v_lshl_add_u64 v[198:199], s[36:37], 0, v[148:149]
	s_addc_u32 s73, s37, 0
	s_add_i32 s74, s75, s29
	global_load_lds_dwordx4 v[198:199], off
	v_lshl_add_u64 v[230:231], s[72:73], 0, v[204:205]
	s_mov_b32 m0, s74
	v_lshl_add_u64 v[232:233], s[44:45], 0, v[146:147]
	global_load_lds_dwordx4 v[230:231], off
	v_lshl_add_u64 v[230:231], s[72:73], 0, v[148:149]
	s_add_i32 m0, s74, 0x2000
	s_nop 0
	global_load_lds_dwordx4 v[230:231], off
	v_lshl_add_u64 v[230:231], s[44:45], 0, v[144:145]
	s_mov_b32 m0, s7
	s_nop 0
	global_load_lds_dwordx4 v[230:231], off
	s_mov_b32 m0, s9
	s_nop 0
	global_load_lds_dwordx4 v[232:233], off
	s_waitcnt vmcnt(8)
	s_waitcnt lgkmcnt(0)
	s_barrier
	s_setprio 1
	v_mfma_f32_16x16x32_bf16 v[60:63], v[132:135], v[186:189], 0
	v_mfma_f32_16x16x32_bf16 v[56:59], v[140:143], v[186:189], 0
	v_mfma_f32_16x16x32_bf16 v[52:55], v[132:135], v[194:197], 0
	v_mfma_f32_16x16x32_bf16 v[48:51], v[140:143], v[194:197], 0
	v_mfma_f32_16x16x32_bf16 v[44:47], v[132:135], v[214:217], 0
	v_mfma_f32_16x16x32_bf16 v[40:43], v[140:143], v[214:217], 0
	v_mfma_f32_16x16x32_bf16 v[36:39], v[132:135], v[222:225], 0
	v_mfma_f32_16x16x32_bf16 v[32:35], v[140:143], v[222:225], 0
	v_mfma_f32_16x16x32_bf16 v[60:63], v[136:139], v[190:193], v[60:63]
	v_mfma_f32_16x16x32_bf16 v[56:59], v[166:169], v[190:193], v[56:59]
	v_mfma_f32_16x16x32_bf16 v[52:55], v[136:139], v[210:213], v[52:55]
	v_mfma_f32_16x16x32_bf16 v[48:51], v[166:169], v[210:213], v[48:51]
	v_mfma_f32_16x16x32_bf16 v[44:47], v[136:139], v[218:221], v[44:47]
	v_mfma_f32_16x16x32_bf16 v[40:43], v[166:169], v[218:221], v[40:43]
	v_mfma_f32_16x16x32_bf16 v[36:39], v[136:139], v[226:229], v[36:39]
	v_mfma_f32_16x16x32_bf16 v[32:35], v[166:169], v[226:229], v[32:35]
	v_mfma_f32_16x16x32_bf16 v[28:31], v[170:173], v[186:189], 0
	v_mfma_f32_16x16x32_bf16 v[24:27], v[178:181], v[186:189], 0
	v_mfma_f32_16x16x32_bf16 v[20:23], v[170:173], v[194:197], 0
	v_mfma_f32_16x16x32_bf16 v[16:19], v[178:181], v[194:197], 0
	v_mfma_f32_16x16x32_bf16 v[12:15], v[170:173], v[214:217], 0
	v_mfma_f32_16x16x32_bf16 v[8:11], v[178:181], v[214:217], 0
	v_mfma_f32_16x16x32_bf16 v[4:7], v[170:173], v[222:225], 0
	v_mfma_f32_16x16x32_bf16 v[0:3], v[178:181], v[222:225], 0
	v_mfma_f32_16x16x32_bf16 v[28:31], v[174:177], v[190:193], v[28:31]
	v_mfma_f32_16x16x32_bf16 v[24:27], v[182:185], v[190:193], v[24:27]
	v_mfma_f32_16x16x32_bf16 v[20:23], v[174:177], v[210:213], v[20:23]
	v_mfma_f32_16x16x32_bf16 v[16:19], v[182:185], v[210:213], v[16:19]
	v_mfma_f32_16x16x32_bf16 v[12:15], v[174:177], v[218:221], v[12:15]
	v_mfma_f32_16x16x32_bf16 v[8:11], v[182:185], v[218:221], v[8:11]
	v_mfma_f32_16x16x32_bf16 v[4:7], v[174:177], v[226:229], v[4:7]
	v_mfma_f32_16x16x32_bf16 v[0:3], v[182:185], v[226:229], v[0:3]
	s_setprio 0
	s_barrier
	s_add_i32 s72, 0, 0x18000
	v_add_u32_e32 v156, s72, v159
	s_add_i32 s73, 0, 0x1c000
	ds_read_b128 v[132:135], v156
	ds_read_b128 v[136:139], v156 offset:1024
	ds_read_b128 v[140:143], v156 offset:2048
	ds_read_b128 v[166:169], v156 offset:3072
	v_add_u32_e32 v156, s73, v159
	ds_read_b128 v[170:173], v156
	ds_read_b128 v[174:177], v156 offset:1024
	ds_read_b128 v[178:181], v156 offset:2048
	ds_read_b128 v[182:185], v156 offset:3072
	s_add_u32 s44, s44, 0x80000
	s_addc_u32 s45, s45, 0
	s_mov_b32 m0, s49
	v_lshl_add_u64 v[248:249], s[44:45], 0, v[144:145]
	ds_read_b128 v[186:189], v165 offset:32768
	ds_read_b128 v[190:193], v165 offset:33792
	ds_read_b128 v[194:197], v165 offset:34816
	ds_read_b128 v[210:213], v165 offset:35840
	ds_read_b128 v[214:217], v165 offset:36864
	ds_read_b128 v[218:221], v165 offset:37888
	ds_read_b128 v[222:225], v165 offset:38912
	ds_read_b128 v[226:229], v165 offset:39936
	global_load_lds_dwordx4 v[248:249], off
	v_lshl_add_u64 v[248:249], s[44:45], 0, v[146:147]
	s_mov_b32 m0, s50
	s_nop 0
	global_load_lds_dwordx4 v[248:249], off
	s_waitcnt vmcnt(8)
	s_waitcnt lgkmcnt(0)
	s_barrier
	s_setprio 1
	v_mfma_f32_16x16x32_bf16 v[124:127], v[132:135], v[186:189], v[124:127]
	v_mfma_f32_16x16x32_bf16 v[120:123], v[140:143], v[186:189], v[120:123]
	v_mfma_f32_16x16x32_bf16 v[116:119], v[132:135], v[194:197], v[116:119]
	v_mfma_f32_16x16x32_bf16 v[112:115], v[140:143], v[194:197], v[112:115]
	v_mfma_f32_16x16x32_bf16 v[108:111], v[132:135], v[214:217], v[108:111]
	v_mfma_f32_16x16x32_bf16 v[104:107], v[140:143], v[214:217], v[104:107]
	v_mfma_f32_16x16x32_bf16 v[100:103], v[132:135], v[222:225], v[100:103]
	v_mfma_f32_16x16x32_bf16 v[96:99], v[140:143], v[222:225], v[96:99]
	v_mfma_f32_16x16x32_bf16 v[124:127], v[136:139], v[190:193], v[124:127]
	v_mfma_f32_16x16x32_bf16 v[120:123], v[166:169], v[190:193], v[120:123]
	v_mfma_f32_16x16x32_bf16 v[116:119], v[136:139], v[210:213], v[116:119]
	v_mfma_f32_16x16x32_bf16 v[112:115], v[166:169], v[210:213], v[112:115]
	v_mfma_f32_16x16x32_bf16 v[108:111], v[136:139], v[218:221], v[108:111]
	v_mfma_f32_16x16x32_bf16 v[104:107], v[166:169], v[218:221], v[104:107]
	v_mfma_f32_16x16x32_bf16 v[100:103], v[136:139], v[226:229], v[100:103]
	v_mfma_f32_16x16x32_bf16 v[96:99], v[166:169], v[226:229], v[96:99]
	v_mfma_f32_16x16x32_bf16 v[92:95], v[170:173], v[186:189], v[92:95]
	v_mfma_f32_16x16x32_bf16 v[88:91], v[178:181], v[186:189], v[88:91]
	v_mfma_f32_16x16x32_bf16 v[84:87], v[170:173], v[194:197], v[84:87]
	v_mfma_f32_16x16x32_bf16 v[80:83], v[178:181], v[194:197], v[80:83]
	v_mfma_f32_16x16x32_bf16 v[76:79], v[170:173], v[214:217], v[76:79]
	v_mfma_f32_16x16x32_bf16 v[72:75], v[178:181], v[214:217], v[72:75]
	v_mfma_f32_16x16x32_bf16 v[68:71], v[170:173], v[222:225], v[68:71]
	v_mfma_f32_16x16x32_bf16 v[64:67], v[178:181], v[222:225], v[64:67]
	v_mfma_f32_16x16x32_bf16 v[92:95], v[174:177], v[190:193], v[92:95]
	v_mfma_f32_16x16x32_bf16 v[88:91], v[182:185], v[190:193], v[88:91]
	v_mfma_f32_16x16x32_bf16 v[84:87], v[174:177], v[210:213], v[84:87]
	v_mfma_f32_16x16x32_bf16 v[80:83], v[182:185], v[210:213], v[80:83]
	v_mfma_f32_16x16x32_bf16 v[76:79], v[174:177], v[218:221], v[76:79]
	v_mfma_f32_16x16x32_bf16 v[72:75], v[182:185], v[218:221], v[72:75]
	v_mfma_f32_16x16x32_bf16 v[68:71], v[174:177], v[226:229], v[68:71]
	v_mfma_f32_16x16x32_bf16 v[64:67], v[182:185], v[226:229], v[64:67]
	s_setprio 0
	s_barrier
	s_add_i32 s44, s72, s29
	v_lshl_add_u64 v[154:155], v[154:155], 0, s[12:13]
	s_mov_b32 m0, s44
	ds_read_b128 v[186:189], v165 offset:49152
	ds_read_b128 v[190:193], v165 offset:50176
	ds_read_b128 v[194:197], v165 offset:51200
	ds_read_b128 v[210:213], v165 offset:52224
	ds_read_b128 v[214:217], v165 offset:53248
	ds_read_b128 v[218:221], v165 offset:54272
	ds_read_b128 v[222:225], v165 offset:55296
	ds_read_b128 v[226:229], v165 offset:56320
	global_load_lds_dwordx4 v[154:155], off
	s_add_i32 m0, s44, 0x2000
	s_add_u32 s36, s36, 0x80080
	v_lshl_add_u64 v[154:155], v[198:199], 0, s[12:13]
	s_addc_u32 s37, s37, 0
	s_add_i32 s44, s73, s29
	global_load_lds_dwordx4 v[154:155], off
	v_lshl_add_u64 v[154:155], s[36:37], 0, v[204:205]
	s_mov_b32 m0, s44
	s_nop 0
	global_load_lds_dwordx4 v[154:155], off
	v_lshl_add_u64 v[154:155], s[36:37], 0, v[148:149]
	s_add_i32 m0, s44, 0x2000
	s_nop 0
	global_load_lds_dwordx4 v[154:155], off
	v_lshl_add_u64 v[154:155], v[230:231], 0, s[12:13]
	s_mov_b32 m0, s54
	s_nop 0
	global_load_lds_dwordx4 v[154:155], off
	v_lshl_add_u64 v[154:155], v[232:233], 0, s[12:13]
	s_mov_b32 m0, s55
	s_nop 0
	global_load_lds_dwordx4 v[154:155], off
	s_waitcnt vmcnt(8)
	s_waitcnt lgkmcnt(0)
	s_barrier
	s_setprio 1
	v_mfma_f32_16x16x32_bf16 v[60:63], v[132:135], v[186:189], v[60:63]
	v_mfma_f32_16x16x32_bf16 v[56:59], v[140:143], v[186:189], v[56:59]
	v_mfma_f32_16x16x32_bf16 v[52:55], v[132:135], v[194:197], v[52:55]
	v_mfma_f32_16x16x32_bf16 v[48:51], v[140:143], v[194:197], v[48:51]
	v_mfma_f32_16x16x32_bf16 v[44:47], v[132:135], v[214:217], v[44:47]
	v_mfma_f32_16x16x32_bf16 v[40:43], v[140:143], v[214:217], v[40:43]
	v_mfma_f32_16x16x32_bf16 v[36:39], v[132:135], v[222:225], v[36:39]
	v_mfma_f32_16x16x32_bf16 v[32:35], v[140:143], v[222:225], v[32:35]
	v_mfma_f32_16x16x32_bf16 v[60:63], v[136:139], v[190:193], v[60:63]
	v_mfma_f32_16x16x32_bf16 v[56:59], v[166:169], v[190:193], v[56:59]
	v_mfma_f32_16x16x32_bf16 v[52:55], v[136:139], v[210:213], v[52:55]
	v_mfma_f32_16x16x32_bf16 v[48:51], v[166:169], v[210:213], v[48:51]
	v_mfma_f32_16x16x32_bf16 v[44:47], v[136:139], v[218:221], v[44:47]
	v_mfma_f32_16x16x32_bf16 v[40:43], v[166:169], v[218:221], v[40:43]
	v_mfma_f32_16x16x32_bf16 v[36:39], v[136:139], v[226:229], v[36:39]
	v_mfma_f32_16x16x32_bf16 v[32:35], v[166:169], v[226:229], v[32:35]
	v_mfma_f32_16x16x32_bf16 v[28:31], v[170:173], v[186:189], v[28:31]
	v_mfma_f32_16x16x32_bf16 v[24:27], v[178:181], v[186:189], v[24:27]
	v_mfma_f32_16x16x32_bf16 v[20:23], v[170:173], v[194:197], v[20:23]
	v_mfma_f32_16x16x32_bf16 v[16:19], v[178:181], v[194:197], v[16:19]
	v_mfma_f32_16x16x32_bf16 v[12:15], v[170:173], v[214:217], v[12:15]
	v_mfma_f32_16x16x32_bf16 v[8:11], v[178:181], v[214:217], v[8:11]
	v_mfma_f32_16x16x32_bf16 v[4:7], v[170:173], v[222:225], v[4:7]
	v_mfma_f32_16x16x32_bf16 v[0:3], v[178:181], v[222:225], v[0:3]
	v_mfma_f32_16x16x32_bf16 v[28:31], v[174:177], v[190:193], v[28:31]
	v_mfma_f32_16x16x32_bf16 v[24:27], v[182:185], v[190:193], v[24:27]
	v_mfma_f32_16x16x32_bf16 v[20:23], v[174:177], v[210:213], v[20:23]
	v_mfma_f32_16x16x32_bf16 v[16:19], v[182:185], v[210:213], v[16:19]
	v_mfma_f32_16x16x32_bf16 v[12:15], v[174:177], v[218:221], v[12:15]
	v_mfma_f32_16x16x32_bf16 v[8:11], v[182:185], v[218:221], v[8:11]
	v_mfma_f32_16x16x32_bf16 v[4:7], v[174:177], v[226:229], v[4:7]
	v_mfma_f32_16x16x32_bf16 v[0:3], v[182:185], v[226:229], v[0:3]
	s_setprio 0
	s_barrier
	s_add_i32 s71, s71, 2
	s_add_u32 s0, s0, 0x100
	s_addc_u32 s1, s1, 0
	s_cmp_gt_u32 s71, 29
	s_cbranch_scc1 .Lpeel_exit_318
	.p2align 6

.LBB0_361:
	s_add_u32 s54, s0, 0x100
	s_addc_u32 s55, s1, 0
	s_ashr_i32 s11, s10, 31
	s_lshl_b64 s[14:15], s[10:11], 20
	s_add_u32 s20, s16, s14
	s_addc_u32 s21, s17, s15
	s_and_b64 s[14:15], s[64:65], exec
	s_cselect_b32 s11, s21, s3
	s_cselect_b32 s22, s20, s2
	s_ashr_i32 s9, s8, 31
	s_lshl_b64 s[14:15], s[8:9], 20
	s_add_u32 s14, s39, s14
	s_addc_u32 s15, s40, s15
	s_and_b64 s[28:29], s[64:65], exec
	s_cselect_b32 s9, s15, s1
	s_cselect_b32 s25, s14, s0
	s_add_u32 s0, s2, 0x80080
	s_addc_u32 s1, s3, 0
	v_lshl_add_u64 v[138:139], s[0:1], 0, v[134:135]
	s_waitcnt lgkmcnt(0)
	v_lshl_add_u64 v[140:141], s[0:1], 0, v[136:137]
	s_mov_b32 s28, -2
	s_mov_b64 s[0:1], 0
	s_add_u32 s29, s2, s0
	s_addc_u32 s34, s3, s1
	s_add_u32 s29, s29, 0x100
	s_addc_u32 s34, s34, 0
	s_add_u32 s56, s54, s0
	s_addc_u32 s35, s55, s1
	s_add_i32 s57, 0, 0x10000
	s_cmpk_eq_i32 s0, 0xf00
	s_cselect_b32 s37, s11, s34
	s_cselect_b32 s36, s22, s29
	v_add_u32_e32 v150, s57, v154
	s_cselect_b32 s35, s9, s35
	s_cselect_b32 s34, s25, s56
	s_add_i32 s29, 0, 0x14000
	ds_read_b128 v[142:145], v150
	ds_read_b128 v[146:149], v150 offset:1024
	ds_read_b128 v[160:163], v150 offset:2048
	ds_read_b128 v[164:167], v150 offset:3072
	v_add_u32_e32 v150, s29, v154
	ds_read_b128 v[168:171], v150
	ds_read_b128 v[172:175], v150 offset:1024
	ds_read_b128 v[176:179], v150 offset:2048
	ds_read_b128 v[180:183], v150 offset:3072
	v_lshl_add_u64 v[150:151], v[138:139], 0, s[0:1]
	s_add_i32 m0, s41, 0xc000
	ds_read_b128 v[184:187], v159
	ds_read_b128 v[188:191], v159 offset:1024
	ds_read_b128 v[192:195], v159 offset:2048
	ds_read_b128 v[196:199], v159 offset:3072
	ds_read_b128 v[210:213], v159 offset:4096
	ds_read_b128 v[214:217], v159 offset:5120
	ds_read_b128 v[218:221], v159 offset:6144
	ds_read_b128 v[222:225], v159 offset:7168
	global_load_lds_dwordx4 v[150:151], off
	v_lshl_add_u64 v[150:151], v[140:141], 0, s[0:1]
	s_add_i32 m0, s41, 0xe000
	s_nop 0
	global_load_lds_dwordx4 v[150:151], off
	s_waitcnt vmcnt(8)
	s_waitcnt lgkmcnt(0)
	s_barrier
	s_setprio 1
	v_mfma_f32_16x16x32_bf16 v[124:127], v[142:145], v[184:187], 0
	v_mfma_f32_16x16x32_bf16 v[120:123], v[160:163], v[184:187], 0
	v_mfma_f32_16x16x32_bf16 v[116:119], v[142:145], v[192:195], 0
	v_mfma_f32_16x16x32_bf16 v[112:115], v[160:163], v[192:195], 0
	v_mfma_f32_16x16x32_bf16 v[108:111], v[142:145], v[210:213], 0
	v_mfma_f32_16x16x32_bf16 v[104:107], v[160:163], v[210:213], 0
	v_mfma_f32_16x16x32_bf16 v[100:103], v[142:145], v[218:221], 0
	v_mfma_f32_16x16x32_bf16 v[96:99], v[160:163], v[218:221], 0
	v_mfma_f32_16x16x32_bf16 v[124:127], v[146:149], v[188:191], v[124:127]
	v_mfma_f32_16x16x32_bf16 v[120:123], v[164:167], v[188:191], v[120:123]
	v_mfma_f32_16x16x32_bf16 v[116:119], v[146:149], v[196:199], v[116:119]
	v_mfma_f32_16x16x32_bf16 v[112:115], v[164:167], v[196:199], v[112:115]
	v_mfma_f32_16x16x32_bf16 v[108:111], v[146:149], v[214:217], v[108:111]
	v_mfma_f32_16x16x32_bf16 v[104:107], v[164:167], v[214:217], v[104:107]
	v_mfma_f32_16x16x32_bf16 v[100:103], v[146:149], v[222:225], v[100:103]
	v_mfma_f32_16x16x32_bf16 v[96:99], v[164:167], v[222:225], v[96:99]
	v_mfma_f32_16x16x32_bf16 v[92:95], v[168:171], v[184:187], 0
	v_mfma_f32_16x16x32_bf16 v[88:91], v[176:179], v[184:187], 0
	v_mfma_f32_16x16x32_bf16 v[84:87], v[168:171], v[192:195], 0
	v_mfma_f32_16x16x32_bf16 v[80:83], v[176:179], v[192:195], 0
	v_mfma_f32_16x16x32_bf16 v[76:79], v[168:171], v[210:213], 0
	v_mfma_f32_16x16x32_bf16 v[72:75], v[176:179], v[210:213], 0
	v_mfma_f32_16x16x32_bf16 v[68:71], v[168:171], v[218:221], 0
	v_mfma_f32_16x16x32_bf16 v[64:67], v[176:179], v[218:221], 0
	v_mfma_f32_16x16x32_bf16 v[92:95], v[172:175], v[188:191], v[92:95]
	v_mfma_f32_16x16x32_bf16 v[88:91], v[180:183], v[188:191], v[88:91]
	v_mfma_f32_16x16x32_bf16 v[84:87], v[172:175], v[196:199], v[84:87]
	v_mfma_f32_16x16x32_bf16 v[80:83], v[180:183], v[196:199], v[80:83]
	v_mfma_f32_16x16x32_bf16 v[76:79], v[172:175], v[214:217], v[76:79]
	v_mfma_f32_16x16x32_bf16 v[72:75], v[180:183], v[214:217], v[72:75]
	v_mfma_f32_16x16x32_bf16 v[68:71], v[172:175], v[222:225], v[68:71]
	v_mfma_f32_16x16x32_bf16 v[64:67], v[180:183], v[222:225], v[64:67]
	s_setprio 0
	s_barrier
	s_add_i32 s56, s57, s38
	v_lshl_add_u64 v[150:151], s[34:35], 0, v[204:205]
	s_mov_b32 m0, s56
	ds_read_b128 v[184:187], v159 offset:16384
	ds_read_b128 v[188:191], v159 offset:17408
	ds_read_b128 v[192:195], v159 offset:18432
	ds_read_b128 v[196:199], v159 offset:19456
	ds_read_b128 v[210:213], v159 offset:20480
	ds_read_b128 v[214:217], v159 offset:21504
	ds_read_b128 v[218:221], v159 offset:22528
	ds_read_b128 v[222:225], v159 offset:23552
	global_load_lds_dwordx4 v[150:151], off
	s_add_i32 m0, s56, 0x2000
	s_add_u32 s56, s34, 0x80000
	v_lshl_add_u64 v[226:227], s[34:35], 0, v[128:129]
	s_addc_u32 s57, s35, 0
	s_add_i32 s29, s29, s38
	global_load_lds_dwordx4 v[226:227], off
	v_lshl_add_u64 v[228:229], s[56:57], 0, v[204:205]
	s_mov_b32 m0, s29
	v_lshl_add_u64 v[230:231], s[36:37], 0, v[130:131]
	global_load_lds_dwordx4 v[228:229], off
	v_lshl_add_u64 v[228:229], s[56:57], 0, v[128:129]
	s_add_i32 m0, s29, 0x2000
	s_nop 0
	global_load_lds_dwordx4 v[228:229], off
	v_lshl_add_u64 v[228:229], s[36:37], 0, v[132:133]
	s_mov_b32 m0, s41
	s_nop 0
	global_load_lds_dwordx4 v[228:229], off
	s_mov_b32 m0, s42
	s_nop 0
	global_load_lds_dwordx4 v[230:231], off
	s_waitcnt vmcnt(8)
	s_waitcnt lgkmcnt(0)
	s_barrier
	s_setprio 1
	v_mfma_f32_16x16x32_bf16 v[60:63], v[142:145], v[184:187], 0
	v_mfma_f32_16x16x32_bf16 v[56:59], v[160:163], v[184:187], 0
	v_mfma_f32_16x16x32_bf16 v[52:55], v[142:145], v[192:195], 0
	v_mfma_f32_16x16x32_bf16 v[48:51], v[160:163], v[192:195], 0
	v_mfma_f32_16x16x32_bf16 v[44:47], v[142:145], v[210:213], 0
	v_mfma_f32_16x16x32_bf16 v[40:43], v[160:163], v[210:213], 0
	v_mfma_f32_16x16x32_bf16 v[36:39], v[142:145], v[218:221], 0
	v_mfma_f32_16x16x32_bf16 v[32:35], v[160:163], v[218:221], 0
	v_mfma_f32_16x16x32_bf16 v[60:63], v[146:149], v[188:191], v[60:63]
	v_mfma_f32_16x16x32_bf16 v[56:59], v[164:167], v[188:191], v[56:59]
	v_mfma_f32_16x16x32_bf16 v[52:55], v[146:149], v[196:199], v[52:55]
	v_mfma_f32_16x16x32_bf16 v[48:51], v[164:167], v[196:199], v[48:51]
	v_mfma_f32_16x16x32_bf16 v[44:47], v[146:149], v[214:217], v[44:47]
	v_mfma_f32_16x16x32_bf16 v[40:43], v[164:167], v[214:217], v[40:43]
	v_mfma_f32_16x16x32_bf16 v[36:39], v[146:149], v[222:225], v[36:39]
	v_mfma_f32_16x16x32_bf16 v[32:35], v[164:167], v[222:225], v[32:35]
	v_mfma_f32_16x16x32_bf16 v[28:31], v[168:171], v[184:187], 0
	v_mfma_f32_16x16x32_bf16 v[24:27], v[176:179], v[184:187], 0
	v_mfma_f32_16x16x32_bf16 v[20:23], v[168:171], v[192:195], 0
	v_mfma_f32_16x16x32_bf16 v[16:19], v[176:179], v[192:195], 0
	v_mfma_f32_16x16x32_bf16 v[12:15], v[168:171], v[210:213], 0
	v_mfma_f32_16x16x32_bf16 v[8:11], v[176:179], v[210:213], 0
	v_mfma_f32_16x16x32_bf16 v[4:7], v[168:171], v[218:221], 0
	v_mfma_f32_16x16x32_bf16 v[0:3], v[176:179], v[218:221], 0
	v_mfma_f32_16x16x32_bf16 v[28:31], v[172:175], v[188:191], v[28:31]
	v_mfma_f32_16x16x32_bf16 v[24:27], v[180:183], v[188:191], v[24:27]
	v_mfma_f32_16x16x32_bf16 v[20:23], v[172:175], v[196:199], v[20:23]
	v_mfma_f32_16x16x32_bf16 v[16:19], v[180:183], v[196:199], v[16:19]
	v_mfma_f32_16x16x32_bf16 v[12:15], v[172:175], v[214:217], v[12:15]
	v_mfma_f32_16x16x32_bf16 v[8:11], v[180:183], v[214:217], v[8:11]
	v_mfma_f32_16x16x32_bf16 v[4:7], v[172:175], v[222:225], v[4:7]
	v_mfma_f32_16x16x32_bf16 v[0:3], v[180:183], v[222:225], v[0:3]
	s_setprio 0
	s_barrier
	s_add_i32 s29, 0, 0x18000
	v_add_u32_e32 v152, s29, v154
	s_add_i32 s56, 0, 0x1c000
	ds_read_b128 v[142:145], v152
	ds_read_b128 v[146:149], v152 offset:1024
	ds_read_b128 v[160:163], v152 offset:2048
	ds_read_b128 v[164:167], v152 offset:3072
	v_add_u32_e32 v152, s56, v154
	ds_read_b128 v[168:171], v152
	ds_read_b128 v[172:175], v152 offset:1024
	ds_read_b128 v[176:179], v152 offset:2048
	ds_read_b128 v[180:183], v152 offset:3072
	s_add_u32 s36, s36, 0x80000
	s_addc_u32 s37, s37, 0
	s_mov_b32 m0, s43
	v_lshl_add_u64 v[232:233], s[36:37], 0, v[132:133]
	ds_read_b128 v[184:187], v159 offset:32768
	ds_read_b128 v[188:191], v159 offset:33792
	ds_read_b128 v[192:195], v159 offset:34816
	ds_read_b128 v[196:199], v159 offset:35840
	ds_read_b128 v[210:213], v159 offset:36864
	ds_read_b128 v[214:217], v159 offset:37888
	ds_read_b128 v[218:221], v159 offset:38912
	ds_read_b128 v[222:225], v159 offset:39936
	global_load_lds_dwordx4 v[232:233], off
	v_lshl_add_u64 v[232:233], s[36:37], 0, v[130:131]
	s_mov_b32 m0, s44
	s_nop 0
	global_load_lds_dwordx4 v[232:233], off
	s_waitcnt vmcnt(8)
	s_waitcnt lgkmcnt(0)
	s_barrier
	s_setprio 1
	v_mfma_f32_16x16x32_bf16 v[124:127], v[142:145], v[184:187], v[124:127]
	v_mfma_f32_16x16x32_bf16 v[120:123], v[160:163], v[184:187], v[120:123]
	v_mfma_f32_16x16x32_bf16 v[116:119], v[142:145], v[192:195], v[116:119]
	v_mfma_f32_16x16x32_bf16 v[112:115], v[160:163], v[192:195], v[112:115]
	v_mfma_f32_16x16x32_bf16 v[108:111], v[142:145], v[210:213], v[108:111]
	v_mfma_f32_16x16x32_bf16 v[104:107], v[160:163], v[210:213], v[104:107]
	v_mfma_f32_16x16x32_bf16 v[100:103], v[142:145], v[218:221], v[100:103]
	v_mfma_f32_16x16x32_bf16 v[96:99], v[160:163], v[218:221], v[96:99]
	v_mfma_f32_16x16x32_bf16 v[124:127], v[146:149], v[188:191], v[124:127]
	v_mfma_f32_16x16x32_bf16 v[120:123], v[164:167], v[188:191], v[120:123]
	v_mfma_f32_16x16x32_bf16 v[116:119], v[146:149], v[196:199], v[116:119]
	v_mfma_f32_16x16x32_bf16 v[112:115], v[164:167], v[196:199], v[112:115]
	v_mfma_f32_16x16x32_bf16 v[108:111], v[146:149], v[214:217], v[108:111]
	v_mfma_f32_16x16x32_bf16 v[104:107], v[164:167], v[214:217], v[104:107]
	v_mfma_f32_16x16x32_bf16 v[100:103], v[146:149], v[222:225], v[100:103]
	v_mfma_f32_16x16x32_bf16 v[96:99], v[164:167], v[222:225], v[96:99]
	v_mfma_f32_16x16x32_bf16 v[92:95], v[168:171], v[184:187], v[92:95]
	v_mfma_f32_16x16x32_bf16 v[88:91], v[176:179], v[184:187], v[88:91]
	v_mfma_f32_16x16x32_bf16 v[84:87], v[168:171], v[192:195], v[84:87]
	v_mfma_f32_16x16x32_bf16 v[80:83], v[176:179], v[192:195], v[80:83]
	v_mfma_f32_16x16x32_bf16 v[76:79], v[168:171], v[210:213], v[76:79]
	v_mfma_f32_16x16x32_bf16 v[72:75], v[176:179], v[210:213], v[72:75]
	v_mfma_f32_16x16x32_bf16 v[68:71], v[168:171], v[218:221], v[68:71]
	v_mfma_f32_16x16x32_bf16 v[64:67], v[176:179], v[218:221], v[64:67]
	v_mfma_f32_16x16x32_bf16 v[92:95], v[172:175], v[188:191], v[92:95]
	v_mfma_f32_16x16x32_bf16 v[88:91], v[180:183], v[188:191], v[88:91]
	v_mfma_f32_16x16x32_bf16 v[84:87], v[172:175], v[196:199], v[84:87]
	v_mfma_f32_16x16x32_bf16 v[80:83], v[180:183], v[196:199], v[80:83]
	v_mfma_f32_16x16x32_bf16 v[76:79], v[172:175], v[214:217], v[76:79]
	v_mfma_f32_16x16x32_bf16 v[72:75], v[180:183], v[214:217], v[72:75]
	v_mfma_f32_16x16x32_bf16 v[68:71], v[172:175], v[222:225], v[68:71]
	v_mfma_f32_16x16x32_bf16 v[64:67], v[180:183], v[222:225], v[64:67]
	s_setprio 0
	s_barrier
	s_add_i32 s29, s29, s38
	v_lshl_add_u64 v[150:151], v[150:151], 0, s[12:13]
	s_mov_b32 m0, s29
	ds_read_b128 v[184:187], v159 offset:49152
	ds_read_b128 v[188:191], v159 offset:50176
	ds_read_b128 v[192:195], v159 offset:51200
	ds_read_b128 v[196:199], v159 offset:52224
	ds_read_b128 v[210:213], v159 offset:53248
	ds_read_b128 v[214:217], v159 offset:54272
	ds_read_b128 v[218:221], v159 offset:55296
	ds_read_b128 v[222:225], v159 offset:56320
	global_load_lds_dwordx4 v[150:151], off
	s_add_i32 m0, s29, 0x2000
	s_add_u32 s34, s34, 0x80080
	v_lshl_add_u64 v[150:151], v[226:227], 0, s[12:13]
	s_addc_u32 s35, s35, 0
	s_add_i32 s29, s56, s38
	global_load_lds_dwordx4 v[150:151], off
	v_lshl_add_u64 v[150:151], s[34:35], 0, v[204:205]
	s_mov_b32 m0, s29
	s_nop 0
	global_load_lds_dwordx4 v[150:151], off
	v_lshl_add_u64 v[150:151], s[34:35], 0, v[128:129]
	s_add_i32 m0, s29, 0x2000
	s_nop 0
	global_load_lds_dwordx4 v[150:151], off
	v_lshl_add_u64 v[150:151], v[228:229], 0, s[12:13]
	s_mov_b32 m0, s46
	s_nop 0
	global_load_lds_dwordx4 v[150:151], off
	v_lshl_add_u64 v[150:151], v[230:231], 0, s[12:13]
	s_mov_b32 m0, s47
	s_nop 0
	global_load_lds_dwordx4 v[150:151], off
	s_waitcnt vmcnt(8)
	s_waitcnt lgkmcnt(0)
	s_barrier
	s_setprio 1
	v_mfma_f32_16x16x32_bf16 v[60:63], v[142:145], v[184:187], v[60:63]
	v_mfma_f32_16x16x32_bf16 v[56:59], v[160:163], v[184:187], v[56:59]
	v_mfma_f32_16x16x32_bf16 v[52:55], v[142:145], v[192:195], v[52:55]
	v_mfma_f32_16x16x32_bf16 v[48:51], v[160:163], v[192:195], v[48:51]
	v_mfma_f32_16x16x32_bf16 v[44:47], v[142:145], v[210:213], v[44:47]
	v_mfma_f32_16x16x32_bf16 v[40:43], v[160:163], v[210:213], v[40:43]
	v_mfma_f32_16x16x32_bf16 v[36:39], v[142:145], v[218:221], v[36:39]
	v_mfma_f32_16x16x32_bf16 v[32:35], v[160:163], v[218:221], v[32:35]
	v_mfma_f32_16x16x32_bf16 v[60:63], v[146:149], v[188:191], v[60:63]
	v_mfma_f32_16x16x32_bf16 v[56:59], v[164:167], v[188:191], v[56:59]
	v_mfma_f32_16x16x32_bf16 v[52:55], v[146:149], v[196:199], v[52:55]
	v_mfma_f32_16x16x32_bf16 v[48:51], v[164:167], v[196:199], v[48:51]
	v_mfma_f32_16x16x32_bf16 v[44:47], v[146:149], v[214:217], v[44:47]
	v_mfma_f32_16x16x32_bf16 v[40:43], v[164:167], v[214:217], v[40:43]
	v_mfma_f32_16x16x32_bf16 v[36:39], v[146:149], v[222:225], v[36:39]
	v_mfma_f32_16x16x32_bf16 v[32:35], v[164:167], v[222:225], v[32:35]
	v_mfma_f32_16x16x32_bf16 v[28:31], v[168:171], v[184:187], v[28:31]
	v_mfma_f32_16x16x32_bf16 v[24:27], v[176:179], v[184:187], v[24:27]
	v_mfma_f32_16x16x32_bf16 v[20:23], v[168:171], v[192:195], v[20:23]
	v_mfma_f32_16x16x32_bf16 v[16:19], v[176:179], v[192:195], v[16:19]
	v_mfma_f32_16x16x32_bf16 v[12:15], v[168:171], v[210:213], v[12:15]
	v_mfma_f32_16x16x32_bf16 v[8:11], v[176:179], v[210:213], v[8:11]
	v_mfma_f32_16x16x32_bf16 v[4:7], v[168:171], v[218:221], v[4:7]
	v_mfma_f32_16x16x32_bf16 v[0:3], v[176:179], v[218:221], v[0:3]
	v_mfma_f32_16x16x32_bf16 v[28:31], v[172:175], v[188:191], v[28:31]
	v_mfma_f32_16x16x32_bf16 v[24:27], v[180:183], v[188:191], v[24:27]
	v_mfma_f32_16x16x32_bf16 v[20:23], v[172:175], v[196:199], v[20:23]
	v_mfma_f32_16x16x32_bf16 v[16:19], v[180:183], v[196:199], v[16:19]
	v_mfma_f32_16x16x32_bf16 v[12:15], v[172:175], v[214:217], v[12:15]
	v_mfma_f32_16x16x32_bf16 v[8:11], v[180:183], v[214:217], v[8:11]
	v_mfma_f32_16x16x32_bf16 v[4:7], v[172:175], v[222:225], v[4:7]
	v_mfma_f32_16x16x32_bf16 v[0:3], v[180:183], v[222:225], v[0:3]
	s_setprio 0
	s_barrier
	s_add_i32 s28, s28, 2
	s_add_u32 s0, s0, 0x100
	s_addc_u32 s1, s1, 0
	s_cmp_gt_u32 s28, 29
	s_cbranch_scc1 .Lpeel_exit_362
	.p2align 6
